# speedup vs baseline: 1.0419x; 1.0054x over previous
; #define LOAD_K(t) do { _Pragma("unroll") for (int i = 0; i < KCH; ++i) kreg[i] = *(const u32x4*)((const char*)kg + (size_t)((t) * 64 + i * RPPK) * (LD * 2) + kvoff); } while (0)
; #define LOAD_V(t) do { _Pragma("unroll") for (int i = 0; i < VCH; ++i) vreg[i] = *(const u32x4*)((const char*)vg + (size_t)((t) * 64 + i * RPPV) * (LD * 2) + vvoff); \
;         if (MODE == 2 && tid < 64) fkreg = X.F2[(size_t)(b * 16 + hd) * SEQ + (t) * 64 + tid]; } while (0)
; #define STORE_K(buf) do { _Pragma("unroll") for (int i = 0; i < KCH; ++i) *(LAS u32x4*)(lds + (buf) * STG + klds + i * RPPK * PK) = kreg[i]; } while (0)
; #define STORE_V(buf) do { _Pragma("unroll") for (int i = 0; i < VCH; ++i) *(LAS u32x4*)(lds + (buf) * STG + vlds + i * RPPV * PV) = vreg[i]; \
;         if (MODE == 2 && tid < 64) fkb[(buf) * 64 + tid] = fkreg; } while (0)
; template <int MODE>
; __device__ __forceinline__ void attn_unit(LAS unsigned char* lds, const bf16_t* __restrict__ qkvz, bf16_t* __restrict__ A2, const int b, const int hd, const int qb, const AttnX& X, const int tid) {
;     ...
;     LOAD_K(TILE(0)); LOAD_V(TILE(0)); STORE_K(0); STORE_V(0);
;     if (PF2 && NT > 1) { LOAD_K(TILE(1)); if (PF2V) LOAD_V(TILE(1)); }
;     __syncthreads();
;     if (MODE == 2) {
;         if (tid < 128) { float qb = te[256]; for (int w = 1; w < 8; ++w) qb = fmaxf(qb, te[256 + w]); float u = -3e38f; for (int tt = 0; tt <= tid; ++tt) u = fmaxf(u, qb * tb[tt] - te[tt]); te[128 + tid] = u; }
;         __syncthreads();
.LBB0_1010:
	s_or_b64 exec, exec, s[10:11]
	s_waitcnt vmcnt(3)
	ds_write_b128 v159, v[2:5]
	s_waitcnt vmcnt(2)
	ds_write_b128 v159, v[6:9] offset:8704
	s_waitcnt vmcnt(1)
	ds_write_b128 v174, v[130:133] offset:17408
	s_waitcnt vmcnt(0)
	ds_write_b128 v174, v[134:137] offset:27648
	s_and_saveexec_b64 s[10:11], s[8:9]
	ds_write_b32 v175, v189
	s_or_b64 exec, exec, s[10:11]
	s_or_b32 s88, s1, 0x80
	s_lshl_b64 s[6:7], s[88:89], 14
	s_or_b32 s88, s1, 0xa0
	v_lshl_add_u64 v[2:3], v[168:169], 0, s[6:7]
	s_lshl_b64 s[6:7], s[88:89], 14
	v_lshl_add_u64 v[4:5], v[168:169], 0, s[6:7]
	global_load_dwordx4 v[138:141], v[2:3], off
	global_load_dwordx4 v[142:145], v[4:5], off
	s_waitcnt lgkmcnt(0)
	s_barrier
	s_and_saveexec_b64 s[10:11], s[28:29]
	s_cbranch_execz .LBB0_1024
	v_mov_b32_e32 v0, 0xff61b1e6
	s_mov_b64 s[18:19], exec
	v_readlane_b32 s6, v254, 59
	v_readlane_b32 s7, v254, 60
	s_and_b64 s[6:7], s[18:19], s[6:7]
	s_mov_b64 exec, s[6:7]
	s_cbranch_execz .LBB0_1023
	v_readlane_b32 s6, v255, 2
	s_mov_b64 s[22:23], -1
	s_nop 0
	v_mov_b32_e32 v0, s6
	ds_read_b128 v[2:5], v0
	v_readlane_b32 s6, v255, 3
	s_waitcnt lgkmcnt(0)
	v_max_f32_e32 v2, v2, v2
	v_mov_b32_e32 v0, s6
	ds_read_b128 v[6:9], v0
	v_max_f32_e32 v0, v3, v3
	v_max_f32_e32 v0, v2, v0
	v_max3_f32 v0, v0, v4, v5
	v_mov_b32_e32 v3, 0
	s_waitcnt lgkmcnt(0)
	v_max3_f32 v0, v0, v6, v7
	v_max3_f32 v2, v0, v8, v9
	v_readlane_b32 s6, v254, 61
	v_add_u32_e32 v3, 0xfffffe00, v176
	v_and_b32_e32 v4, 63, v158
	ds_read_b32 v6, v3
	ds_read_b32 v7, v176
	v_lshl_add_u32 v5, v4, 2, s6
	v_add_u32_e32 v4, 0xfffffe00, v5
	ds_read_b32 v8, v4
	ds_read_b32 v9, v5
	s_waitcnt lgkmcnt(2)
	v_fma_f32 v10, v2, v6, -v7
	s_waitcnt lgkmcnt(0)
	v_fma_f32 v11, v2, v8, -v9
	s_nop 1
	v_max_f32_dpp v10, v10, v10 row_shr:1 row_mask:0xf bank_mask:0xf
	v_max_f32_dpp v11, v11, v11 row_shr:1 row_mask:0xf bank_mask:0xf
	s_nop 1
	v_max_f32_dpp v10, v10, v10 row_shr:2 row_mask:0xf bank_mask:0xf
	v_max_f32_dpp v11, v11, v11 row_shr:2 row_mask:0xf bank_mask:0xf
	s_nop 1
	v_max_f32_dpp v10, v10, v10 row_shr:4 row_mask:0xf bank_mask:0xf
	v_max_f32_dpp v11, v11, v11 row_shr:4 row_mask:0xf bank_mask:0xf
	s_nop 1
	v_max_f32_dpp v10, v10, v10 row_shr:8 row_mask:0xf bank_mask:0xf
	v_max_f32_dpp v11, v11, v11 row_shr:8 row_mask:0xf bank_mask:0xf
	s_nop 1
	v_max_f32_dpp v10, v10, v10 row_bcast:15 row_mask:0xa bank_mask:0xf
	v_max_f32_dpp v11, v11, v11 row_bcast:15 row_mask:0xa bank_mask:0xf
	s_nop 1
	v_max_f32_dpp v10, v10, v10 row_bcast:31 row_mask:0xc bank_mask:0xf
	v_max_f32_dpp v11, v11, v11 row_bcast:31 row_mask:0xc bank_mask:0xf
	v_mov_b32_e32 v0, 0xff61b1e6
	v_cmp_lt_u32_e32 vcc, 63, v158
	v_readlane_b32 s6, v11, 63
	s_nop 3
	v_mov_b32_e32 v3, s6
	v_cndmask_b32_e32 v0, v0, v3, vcc
	v_max_f32_e32 v0, v0, v10
